# hand-written residual epilogue (bf16 residual phases): waves 1..7 issue XB stores after the XN stores and the phase-end / grid-barrier waits leave those 16 stores in flight (they drain during the barr
# baseline (speedup 1.0000x reference)
; #define LAS __attribute__((address_space(3)))
; __device__ __forceinline__ unsigned xb_add(unsigned* p, unsigned v) { return __hip_atomic_fetch_add(p, v, __ATOMIC_RELAXED, __HIP_MEMORY_SCOPE_AGENT); }
; __device__ __forceinline__ unsigned xb_xcc_id() { return (unsigned)__builtin_amdgcn_s_getreg((3 << 11) | 20) & 0xFu; }
; __device__ __forceinline__ XcdBarrier xcd_barrier_post(unsigned* bar, volatile LAS unsigned* st) {
;     XcdBarrier b; b.bar = bar; b.x = xb_xcc_id(); b.st = st;
;     if (threadIdx.x == 0) (void)xb_add(&bar[XB_XCNT(b.x)], 1u);
;     return b;
; __global__ void __launch_bounds__(NTHREADS) fwd_megakernel(Params p) {
;     ...
;     LAS unsigned char* lds = (LAS unsigned char*)lds_raw;
;     unsigned char* ws = p.ws;
;     bf16_t* XB = (bf16_t*)(ws + WS_X);
;     volatile LAS unsigned* bst = (volatile LAS unsigned*)(lds + 143360);
;     if (threadIdx.x < 2) bst[threadIdx.x] = 0u;
;     __syncthreads();
;     const XcdBarrier gbar = xcd_barrier_post((unsigned*)(ws + WS_CTL), bst);
_Z14fwd_megakernel6Params:
	s_load_dwordx4 s[88:91], s[0:1], 0x80
	v_and_b32_e32 v185, 0x3ff, v0
	s_mov_b32 s63, s2
	s_mov_b32 s101, 0
	v_cmp_gt_u32_e32 vcc, 2, v185
	s_and_saveexec_b64 s[2:3], vcc
	v_lshl_add_u32 v1, v185, 2, 0
	v_add_u32_e32 v1, 0x23000, v1
	v_mov_b32_e32 v2, 0
	ds_write_b32 v1, v2
	s_or_b64 exec, exec, s[2:3]
	s_waitcnt lgkmcnt(0)
	s_barrier
	s_add_u32 s2, s88, 0x40a80000
	s_getreg_b32 s4, hwreg(HW_REG_XCC_ID, 0, 4)
	s_addc_u32 s3, s89, 0
	s_and_b32 s4, s4, 15
	v_cmp_eq_u32_e64 s[8:9], 0, v185
	s_mov_b64 s[6:7], exec
	s_nop 0
	v_writelane_b32 v252, s8, 0
	s_nop 1
	v_writelane_b32 v252, s9, 1
	s_and_b64 s[8:9], s[6:7], s[8:9]
	s_mov_b64 exec, s[8:9]
	s_cbranch_execz .LBB0_5
	s_mov_b64 s[8:9], exec
	v_mbcnt_lo_u32_b32 v1, s8, 0
	v_mbcnt_hi_u32_b32 v1, s9, v1
	v_cmp_eq_u32_e32 vcc, 0, v1
	s_and_b64 s[10:11], exec, vcc
	s_mov_b64 exec, s[10:11]
	s_cbranch_execz .LBB0_5
	s_lshl_b32 s5, s4, 8
	s_bcnt1_i32_b64 s8, s[8:9]
	v_mov_b32_e32 v1, s5
	v_mov_b32_e32 v2, s8
	global_atomic_add v1, v2, s[2:3] offset:1024

; #define PG8_WAIT_V(n) asm volatile("s_waitcnt vmcnt(" #n ")" ::: "memory")
; #define PG8_BAR __builtin_amdgcn_s_barrier()
;     ...
;     PG8_WAIT_V(0);
;     PG8_BAR;
.Lln_ret:
	v_readlane_b32 s0, v254, 54
	v_readlane_b32 s1, v254, 55
	s_andn2_b64 vcc, exec, s[0:1]
	s_cbranch_vccnz .LBB0_281
	s_barrier
	s_branch .LBB0_281
.LBB0_340:
	s_branch .Lw0_a
.Lw0_a_ret:
	v_readlane_b32 s63, v254, 7
	s_movk_i32 s67, 0x3ff
	v_readlane_b32 s55, v254, 10
	v_readlane_b32 s20, v254, 11
	v_readlane_b32 s26, v254, 47
	v_readlane_b32 s27, v254, 53
	s_barrier

; __device__ __forceinline__ void xcd_barrier(const XcdBarrier& b) {
;     asm volatile("s_waitcnt vmcnt(0)" ::: "memory");
;     __syncthreads();
;     if (threadIdx.x == 0) {
;         unsigned* bar = b.bar;
;         __builtin_amdgcn_s_waitcnt(0);
;         unsigned nloc = b.st[0], nx = b.st[1];
;         if (nloc == 0u) { xcd_barrier_complete(bar, b.x, nloc, nx); b.st[0] = nloc; b.st[1] = nx; }
.Lln_latch_ret:
	s_cmp_ge_i32 s90, s91
	s_cselect_b64 s[0:1], -1, 0
	s_cmp_lt_i32 s90, s91
	s_cselect_b64 s[2:3], -1, 0
	s_and_b64 s[2:3], s[2:3], s[6:7]
	s_andn2_b64 vcc, exec, s[2:3]
	s_cbranch_vccnz .LBB0_10
	v_readlane_b32 s6, v252, 34
	v_readlane_b32 s7, v252, 35
	s_mov_b64 s[2:3], -1
	s_and_b64 vcc, exec, s[6:7]
	s_cbranch_vccz .LBB0_668
	s_nop 0
	s_branch .Lw0_b
.Lw0_b_ret:
	s_barrier
	s_mov_b64 s[2:3], exec
	v_readlane_b32 s6, v252, 0
	v_readlane_b32 s7, v252, 1
	s_and_b64 s[6:7], s[2:3], s[6:7]
	s_mov_b64 exec, s[6:7]
	s_cbranch_execz .LBB0_667
	v_readlane_b32 s6, v253, 51
	s_waitcnt vmcnt(0) expcnt(0) lgkmcnt(0)
	s_nop 0
	v_mov_b32_e32 v0, s6
	ds_read_b32 v2, v0
	v_readlane_b32 s6, v253, 52
	s_waitcnt lgkmcnt(0)
	v_cmp_ne_u32_e32 vcc, 0, v2
	v_mov_b32_e32 v0, s6
	ds_read_b32 v0, v0
	s_cbranch_vccnz .LBB0_630
	v_readlane_b32 s8, v252, 2
	v_readlane_b32 s9, v252, 3
	s_load_dwordx2 s[6:7], s[8:9], 0x0
	s_nop 0
	s_load_dword s8, s[8:9], 0x8
	s_mov_b32 s13, 1
	s_waitcnt lgkmcnt(0)
	s_mul_i32 s12, s7, s6
	s_mul_i32 s12, s12, s8
	s_branch .LBB0_618

; __global__ void __launch_bounds__(NTHREADS) fwd_megakernel(Params p) {
;     ...
;             if (k == 0) { if (l > 0) phase_rmsnorm<false, true>(XB, p.norm_mix + (size_t)l * DM, ws + WS_XN); else need_bar = false; }
;             else if (k == 1) { S.kind = 0; S.A0 = (const char*)(ws + WS_XN); S.B0 = (const char*)(ws + WS_WIN + l * SZ_WIN); S.O0 = (char*)(ws + WS_Z);
;                 S.A1 = (const char*)(ws + WS_WF + l * SZ_WF); S.B1 = (const char*)(ws + WS_XN); S.O1 = (char*)(ws + WS_T); }
;             else if (k == 2) { S.kind = 2; S.A0 = (const char*)(ws + WS_DFT); S.B0 = (const char*)(ws + WS_T); S.O0 = (char*)(ws + WS_CP); lda = 8192; ldb = 8192; epi = 0; }
;             else if (k == 3) phase_mixnorm(p, l);
;             else if (k == 4) { S.kind = 3; S.A0 = (const char*)(ws + WS_MIX); S.B0 = (const char*)(ws + WS_WOUT + l * SZ_WOUT); S.O0 = (char*)XB; S.R0 = (l == 0) ? p.x : (const float*)XB; S.r32 = (l == 0) ? 1 : 0; S.nM = 32; S.nN = 8; epi = 1; }
;             else if (k == 5) phase_rmsnorm<false, true>(XB, p.norm_ffn + (size_t)l * DM, ws + WS_XN);
.Lln_end:
	s_movk_i32 s56, 0x1f8
	s_movk_i32 s57, 0x1fff
	s_mov_b32 s58, 0x2c000
	s_mov_b32 s59, 0x84000
	s_mov_b32 s64, 0xb0000
	s_mov_b32 s65, 0xdc000
	s_mov_b64 vcc, s[100:101]
	s_mov_b32 s101, 0
	s_cbranch_vccnz .LBB0_282
	s_branch .Lln_ret

; __device__ __forceinline__ unsigned cvt_pk_bf16(float lo, float hi) { unsigned r; asm volatile("v_cvt_pk_bf16_f32 %0, %1, %2" : "=v"(r) : "v"(lo), "v"(hi)); return r; }
;     __device__ __forceinline__ void operator()(const f32x4 (&acc)[2][2][4][2], const Unit& u, int wr, int wc, int fr_in, int fq_in) const {
;     ...
;                 for (int m2 = 0; m2 < 2; ++m2) { const int m = 2 * mh + m2; const size_t off = off0 + (size_t)(ai * HALF + m * 16) * u.ldc;
; #pragma unroll
;                     for (int bj = 0; bj < 2; ++bj) { const f32x4 v0 = acc[ai][bj][m][0] + rv[m2][bj][0], v1 = acc[ai][bj][m][1] + rv[m2][bj][1];
;                         u32x4 w; w.x = cvt_pk_bf16(v0[0], v0[1]); w.y = cvt_pk_bf16(v0[2], v0[3]); w.z = cvt_pk_bf16(v1[0], v1[1]); w.w = cvt_pk_bf16(v1[2], v1[3]);
;                         *(u32x4*)(O + off + bj * HALF) = w; } }
; template <bool OUT_F32, bool IN_BF16>
; __device__ __forceinline__ void phase_rmsnorm(const void* Xv, const float* gain, void* out) {
;     ...
;     f32x4 g[4][2];
; #pragma unroll
;     for (int j = 0; j < 4; ++j) { g[j][0] = *(const f32x4*)(gain + 8 * lane + 512 * j); g[j][1] = *(const f32x4*)(gain + 8 * lane + 512 * j + 4); }
.Lep_pub_done:
	s_or_b64 exec, exec, s[64:65]
	s_barrier
	v_cmp_eq_u32_e32 vcc, 0, v185
	s_and_saveexec_b64 s[64:65], vcc
	global_atomic_add v183, v33, s[58:59]
	s_or_b64 exec, exec, s[64:65]
	global_load_dwordx4 v[88:91], v41, s[56:57]
	global_load_dwordx4 v[80:83], v41, s[56:57] offset:16
	global_load_dwordx4 v[72:75], v41, s[56:57] offset:512
	global_load_dwordx4 v[64:67], v41, s[56:57] offset:528
	v_cmp_gt_u32_e32 vcc, 64, v185
	s_cbranch_vccz .Lep_xb_late
	s_mov_b32 s0, 0x10000
	s_mov_b32 s1, 0
	v_mov_b32_e32 v0, v174
	v_mov_b32_e32 v1, v175
	global_store_dwordx4 v[0:1], v[124:127], off
	global_store_dwordx4 v[0:1], v[92:95], off offset:256
	v_lshl_add_u64 v[0:1], v[0:1], 0, s[0:1]
	global_store_dwordx4 v[0:1], v[116:119], off
	global_store_dwordx4 v[0:1], v[84:87], off offset:256
	v_lshl_add_u64 v[0:1], v[0:1], 0, s[0:1]
	global_store_dwordx4 v[0:1], v[108:111], off
	global_store_dwordx4 v[0:1], v[76:79], off offset:256
	v_lshl_add_u64 v[0:1], v[0:1], 0, s[0:1]
	global_store_dwordx4 v[0:1], v[100:103], off
	global_store_dwordx4 v[0:1], v[68:71], off offset:256
	s_mov_b32 s0, 0x50000
	v_lshl_add_u64 v[0:1], v[0:1], 0, s[0:1]
	s_mov_b32 s0, 0x10000
	global_store_dwordx4 v[0:1], v[60:63], off
	global_store_dwordx4 v[0:1], v[28:31], off offset:256
	v_lshl_add_u64 v[0:1], v[0:1], 0, s[0:1]
	global_store_dwordx4 v[0:1], v[52:55], off
	global_store_dwordx4 v[0:1], v[20:23], off offset:256
	v_lshl_add_u64 v[0:1], v[0:1], 0, s[0:1]
	global_store_dwordx4 v[0:1], v[44:47], off
	global_store_dwordx4 v[0:1], v[12:15], off offset:256
	v_lshl_add_u64 v[0:1], v[0:1], 0, s[0:1]
	global_store_dwordx4 v[0:1], v[36:39], off
	global_store_dwordx4 v[0:1], v[4:7], off offset:256
.Lep_xb_late:
	v_cmp_eq_u32_e32 vcc, 0, v185
	s_and_saveexec_b64 s[64:65], vcc
	s_cbranch_execz .Lep_wait_done
	s_mov_b32 s1, 0

; __device__ __forceinline__ unsigned pk2(float lo, float hi) { const f32x2 v = {lo, hi}; const hwbf16x2 b = __builtin_convertvector(v, hwbf16x2); return __builtin_bit_cast(unsigned, b); }
; template <bool OUT_F32, bool IN_BF16>
; __device__ __forceinline__ void phase_rmsnorm(const void* Xv, const float* gain, void* out) {
;     ...
;         for (int r = 0; r < RPT; ++r) { const int m = m0 + r * NGW; if (m >= NTOK) continue;
; #pragma unroll
;             for (int j = 0; j < 4; ++j) { const f32x4 y0 = v[r][j][0] * rs[r] * g[j][0], y1 = v[r][j][1] * rs[r] * g[j][1];
;                 if (OUT_F32) { float* o = (float*)out + (size_t)m * DM + 8 * lane + 512 * j; *(f32x4*)o = y0; *(f32x4*)(o + 4) = y1; }
;                 else { u32x4 w; w.x = pk2(y0.x, y0.y); w.y = pk2(y0.z, y0.w); w.z = pk2(y1.x, y1.y); w.w = pk2(y1.z, y1.w); *(u32x4*)((bf16_t*)out + (size_t)m * DM + 8 * lane + 512 * j) = w; } } }
.Lep_rs_done:
	s_or_b64 exec, exec, s[64:65]
	s_waitcnt lgkmcnt(0)
	s_barrier
	v_lshlrev_b32_e32 v2, 2, v40
	v_add_u32_e32 v2, 0x21000, v2
	ds_read_b32 v56, v2 offset:0
	ds_read_b32 v57, v2 offset:64
	ds_read_b32 v58, v2 offset:128
	ds_read_b32 v59, v2 offset:192
	ds_read_b32 v48, v2 offset:512
	ds_read_b32 v49, v2 offset:576
	ds_read_b32 v50, v2 offset:640
	ds_read_b32 v51, v2 offset:704
	s_mov_b32 s64, 0x4000000
	s_mov_b32 s65, 0
	v_lshl_add_u64 v[0:1], v[174:175], 0, s[64:65]
	s_mov_b32 s64, 0x10000
	s_waitcnt vmcnt(0) lgkmcnt(0)
	v_lshlrev_b32_e32 v120, 16, v124
	v_and_b32_e32 v121, 0xffff0000, v124
	v_lshlrev_b32_e32 v122, 16, v125
	v_and_b32_e32 v123, 0xffff0000, v125
	v_lshlrev_b32_e32 v112, 16, v126
	v_and_b32_e32 v113, 0xffff0000, v126
	v_lshlrev_b32_e32 v114, 16, v127
	v_and_b32_e32 v115, 0xffff0000, v127
	v_mul_f32_e32 v120, v120, v56
	v_mul_f32_e32 v121, v121, v56
	v_mul_f32_e32 v122, v122, v56
	v_mul_f32_e32 v123, v123, v56
	v_mul_f32_e32 v112, v112, v56
	v_mul_f32_e32 v113, v113, v56
	v_mul_f32_e32 v114, v114, v56
	v_mul_f32_e32 v115, v115, v56
	v_pk_mul_f32 v[120:121], v[120:121], v[88:89]
	v_pk_mul_f32 v[122:123], v[122:123], v[90:91]
	v_pk_mul_f32 v[112:113], v[112:113], v[80:81]
	v_pk_mul_f32 v[114:115], v[114:115], v[82:83]
	v_cvt_pk_bf16_f32 v8, v120, v121
	v_cvt_pk_bf16_f32 v9, v122, v123
	v_cvt_pk_bf16_f32 v10, v112, v113
	v_cvt_pk_bf16_f32 v11, v114, v115
	global_store_dwordx4 v[0:1], v[8:11], off
	v_lshlrev_b32_e32 v120, 16, v92
	v_and_b32_e32 v121, 0xffff0000, v92
	v_lshlrev_b32_e32 v122, 16, v93
	v_and_b32_e32 v123, 0xffff0000, v93
	v_lshlrev_b32_e32 v112, 16, v94
	v_and_b32_e32 v113, 0xffff0000, v94
	v_lshlrev_b32_e32 v114, 16, v95
	v_and_b32_e32 v115, 0xffff0000, v95
	v_mul_f32_e32 v120, v120, v56
	v_mul_f32_e32 v121, v121, v56
	v_mul_f32_e32 v122, v122, v56
	v_mul_f32_e32 v123, v123, v56
	v_mul_f32_e32 v112, v112, v56
	v_mul_f32_e32 v113, v113, v56
	v_mul_f32_e32 v114, v114, v56
	v_mul_f32_e32 v115, v115, v56
	v_pk_mul_f32 v[120:121], v[120:121], v[72:73]
	v_pk_mul_f32 v[122:123], v[122:123], v[74:75]
	v_pk_mul_f32 v[112:113], v[112:113], v[64:65]
	v_pk_mul_f32 v[114:115], v[114:115], v[66:67]
	v_cvt_pk_bf16_f32 v8, v120, v121
	v_cvt_pk_bf16_f32 v9, v122, v123
	v_cvt_pk_bf16_f32 v10, v112, v113
	v_cvt_pk_bf16_f32 v11, v114, v115
	global_store_dwordx4 v[0:1], v[8:11], off offset:256
	v_lshl_add_u64 v[0:1], v[0:1], 0, s[64:65]
	v_lshlrev_b32_e32 v120, 16, v116
	v_and_b32_e32 v121, 0xffff0000, v116
	v_lshlrev_b32_e32 v122, 16, v117
	v_and_b32_e32 v123, 0xffff0000, v117
	v_lshlrev_b32_e32 v112, 16, v118
	v_and_b32_e32 v113, 0xffff0000, v118
	v_lshlrev_b32_e32 v114, 16, v119
	v_and_b32_e32 v115, 0xffff0000, v119
	v_mul_f32_e32 v120, v120, v57
	v_mul_f32_e32 v121, v121, v57
	v_mul_f32_e32 v122, v122, v57
	v_mul_f32_e32 v123, v123, v57
	v_mul_f32_e32 v112, v112, v57
	v_mul_f32_e32 v113, v113, v57
	v_mul_f32_e32 v114, v114, v57
	v_mul_f32_e32 v115, v115, v57
	v_pk_mul_f32 v[120:121], v[120:121], v[88:89]
	v_pk_mul_f32 v[122:123], v[122:123], v[90:91]
	v_pk_mul_f32 v[112:113], v[112:113], v[80:81]
	v_pk_mul_f32 v[114:115], v[114:115], v[82:83]
	v_cvt_pk_bf16_f32 v8, v120, v121
	v_cvt_pk_bf16_f32 v9, v122, v123
	v_cvt_pk_bf16_f32 v10, v112, v113
	v_cvt_pk_bf16_f32 v11, v114, v115
	global_store_dwordx4 v[0:1], v[8:11], off
	v_lshlrev_b32_e32 v120, 16, v84
	v_and_b32_e32 v121, 0xffff0000, v84
	v_lshlrev_b32_e32 v122, 16, v85
	v_and_b32_e32 v123, 0xffff0000, v85
	v_lshlrev_b32_e32 v112, 16, v86
	v_and_b32_e32 v113, 0xffff0000, v86
	v_lshlrev_b32_e32 v114, 16, v87
	v_and_b32_e32 v115, 0xffff0000, v87
	v_mul_f32_e32 v120, v120, v57
	v_mul_f32_e32 v121, v121, v57
	v_mul_f32_e32 v122, v122, v57
	v_mul_f32_e32 v123, v123, v57
	v_mul_f32_e32 v112, v112, v57
	v_mul_f32_e32 v113, v113, v57
	v_mul_f32_e32 v114, v114, v57
	v_mul_f32_e32 v115, v115, v57
	v_pk_mul_f32 v[120:121], v[120:121], v[72:73]
	v_pk_mul_f32 v[122:123], v[122:123], v[74:75]
	v_pk_mul_f32 v[112:113], v[112:113], v[64:65]
	v_pk_mul_f32 v[114:115], v[114:115], v[66:67]
	v_cvt_pk_bf16_f32 v8, v120, v121
	v_cvt_pk_bf16_f32 v9, v122, v123
	v_cvt_pk_bf16_f32 v10, v112, v113
	v_cvt_pk_bf16_f32 v11, v114, v115
	global_store_dwordx4 v[0:1], v[8:11], off offset:256
	v_lshl_add_u64 v[0:1], v[0:1], 0, s[64:65]
	v_lshlrev_b32_e32 v120, 16, v108
	v_and_b32_e32 v121, 0xffff0000, v108
	v_lshlrev_b32_e32 v122, 16, v109
	v_and_b32_e32 v123, 0xffff0000, v109
	v_lshlrev_b32_e32 v112, 16, v110
	v_and_b32_e32 v113, 0xffff0000, v110
	v_lshlrev_b32_e32 v114, 16, v111
	v_and_b32_e32 v115, 0xffff0000, v111
	v_mul_f32_e32 v120, v120, v58
	v_mul_f32_e32 v121, v121, v58
	v_mul_f32_e32 v122, v122, v58
	v_mul_f32_e32 v123, v123, v58
	v_mul_f32_e32 v112, v112, v58
	v_mul_f32_e32 v113, v113, v58
	v_mul_f32_e32 v114, v114, v58
	v_mul_f32_e32 v115, v115, v58
	v_pk_mul_f32 v[120:121], v[120:121], v[88:89]
	v_pk_mul_f32 v[122:123], v[122:123], v[90:91]
	v_pk_mul_f32 v[112:113], v[112:113], v[80:81]
	v_pk_mul_f32 v[114:115], v[114:115], v[82:83]
	v_cvt_pk_bf16_f32 v8, v120, v121
	v_cvt_pk_bf16_f32 v9, v122, v123
	v_cvt_pk_bf16_f32 v10, v112, v113
	v_cvt_pk_bf16_f32 v11, v114, v115
	global_store_dwordx4 v[0:1], v[8:11], off
	v_lshlrev_b32_e32 v120, 16, v76
	v_and_b32_e32 v121, 0xffff0000, v76
	v_lshlrev_b32_e32 v122, 16, v77
	v_and_b32_e32 v123, 0xffff0000, v77
	v_lshlrev_b32_e32 v112, 16, v78
	v_and_b32_e32 v113, 0xffff0000, v78
	v_lshlrev_b32_e32 v114, 16, v79
	v_and_b32_e32 v115, 0xffff0000, v79
	v_mul_f32_e32 v120, v120, v58
	v_mul_f32_e32 v121, v121, v58
	v_mul_f32_e32 v122, v122, v58
	v_mul_f32_e32 v123, v123, v58
	v_mul_f32_e32 v112, v112, v58
	v_mul_f32_e32 v113, v113, v58
	v_mul_f32_e32 v114, v114, v58
; __device__ __forceinline__ unsigned pk2(float lo, float hi) { const f32x2 v = {lo, hi}; const hwbf16x2 b = __builtin_convertvector(v, hwbf16x2); return __builtin_bit_cast(unsigned, b); }
; template <bool OUT_F32, bool IN_BF16>
; __device__ __forceinline__ void phase_rmsnorm(const void* Xv, const float* gain, void* out) {
;     ...
;         for (int r = 0; r < RPT; ++r) { const int m = m0 + r * NGW; if (m >= NTOK) continue;
; #pragma unroll
;             for (int j = 0; j < 4; ++j) { const f32x4 y0 = v[r][j][0] * rs[r] * g[j][0], y1 = v[r][j][1] * rs[r] * g[j][1];
;                 if (OUT_F32) { float* o = (float*)out + (size_t)m * DM + 8 * lane + 512 * j; *(f32x4*)o = y0; *(f32x4*)(o + 4) = y1; }
;                 else { u32x4 w; w.x = pk2(y0.x, y0.y); w.y = pk2(y0.z, y0.w); w.z = pk2(y1.x, y1.y); w.w = pk2(y1.z, y1.w); *(u32x4*)((bf16_t*)out + (size_t)m * DM + 8 * lane + 512 * j) = w; } } }
	v_mul_f32_e32 v115, v115, v58
	v_pk_mul_f32 v[120:121], v[120:121], v[72:73]
	v_pk_mul_f32 v[122:123], v[122:123], v[74:75]
	v_pk_mul_f32 v[112:113], v[112:113], v[64:65]
	v_pk_mul_f32 v[114:115], v[114:115], v[66:67]
	v_cvt_pk_bf16_f32 v8, v120, v121
	v_cvt_pk_bf16_f32 v9, v122, v123
	v_cvt_pk_bf16_f32 v10, v112, v113
	v_cvt_pk_bf16_f32 v11, v114, v115
	global_store_dwordx4 v[0:1], v[8:11], off offset:256
	v_lshl_add_u64 v[0:1], v[0:1], 0, s[64:65]
	v_lshlrev_b32_e32 v120, 16, v100
	v_and_b32_e32 v121, 0xffff0000, v100
	v_lshlrev_b32_e32 v122, 16, v101
	v_and_b32_e32 v123, 0xffff0000, v101
	v_lshlrev_b32_e32 v112, 16, v102
	v_and_b32_e32 v113, 0xffff0000, v102
	v_lshlrev_b32_e32 v114, 16, v103
	v_and_b32_e32 v115, 0xffff0000, v103
	v_mul_f32_e32 v120, v120, v59
	v_mul_f32_e32 v121, v121, v59
	v_mul_f32_e32 v122, v122, v59
	v_mul_f32_e32 v123, v123, v59
	v_mul_f32_e32 v112, v112, v59
	v_mul_f32_e32 v113, v113, v59
	v_mul_f32_e32 v114, v114, v59
	v_mul_f32_e32 v115, v115, v59
	v_pk_mul_f32 v[120:121], v[120:121], v[88:89]
	v_pk_mul_f32 v[122:123], v[122:123], v[90:91]
	v_pk_mul_f32 v[112:113], v[112:113], v[80:81]
	v_pk_mul_f32 v[114:115], v[114:115], v[82:83]
	v_cvt_pk_bf16_f32 v8, v120, v121
	v_cvt_pk_bf16_f32 v9, v122, v123
	v_cvt_pk_bf16_f32 v10, v112, v113
	v_cvt_pk_bf16_f32 v11, v114, v115
	global_store_dwordx4 v[0:1], v[8:11], off
	v_lshlrev_b32_e32 v120, 16, v68
	v_and_b32_e32 v121, 0xffff0000, v68
	v_lshlrev_b32_e32 v122, 16, v69
	v_and_b32_e32 v123, 0xffff0000, v69
	v_lshlrev_b32_e32 v112, 16, v70
	v_and_b32_e32 v113, 0xffff0000, v70
	v_lshlrev_b32_e32 v114, 16, v71
	v_and_b32_e32 v115, 0xffff0000, v71
	v_mul_f32_e32 v120, v120, v59
	v_mul_f32_e32 v121, v121, v59
	v_mul_f32_e32 v122, v122, v59
	v_mul_f32_e32 v123, v123, v59
	v_mul_f32_e32 v112, v112, v59
	v_mul_f32_e32 v113, v113, v59
	v_mul_f32_e32 v114, v114, v59
	v_mul_f32_e32 v115, v115, v59
	v_pk_mul_f32 v[120:121], v[120:121], v[72:73]
	v_pk_mul_f32 v[122:123], v[122:123], v[74:75]
	v_pk_mul_f32 v[112:113], v[112:113], v[64:65]
	v_pk_mul_f32 v[114:115], v[114:115], v[66:67]
	v_cvt_pk_bf16_f32 v8, v120, v121
	v_cvt_pk_bf16_f32 v9, v122, v123
	v_cvt_pk_bf16_f32 v10, v112, v113
	v_cvt_pk_bf16_f32 v11, v114, v115
	global_store_dwordx4 v[0:1], v[8:11], off offset:256
	s_mov_b32 s64, 0x50000
	v_lshl_add_u64 v[0:1], v[0:1], 0, s[64:65]
	s_mov_b32 s64, 0x10000
	v_lshlrev_b32_e32 v120, 16, v60
	v_and_b32_e32 v121, 0xffff0000, v60
	v_lshlrev_b32_e32 v122, 16, v61
	v_and_b32_e32 v123, 0xffff0000, v61
	v_lshlrev_b32_e32 v112, 16, v62
	v_and_b32_e32 v113, 0xffff0000, v62
	v_lshlrev_b32_e32 v114, 16, v63
	v_and_b32_e32 v115, 0xffff0000, v63
	v_mul_f32_e32 v120, v120, v48
	v_mul_f32_e32 v121, v121, v48
	v_mul_f32_e32 v122, v122, v48
	v_mul_f32_e32 v123, v123, v48
	v_mul_f32_e32 v112, v112, v48
	v_mul_f32_e32 v113, v113, v48
	v_mul_f32_e32 v114, v114, v48
	v_mul_f32_e32 v115, v115, v48
	v_pk_mul_f32 v[120:121], v[120:121], v[88:89]
	v_pk_mul_f32 v[122:123], v[122:123], v[90:91]
	v_pk_mul_f32 v[112:113], v[112:113], v[80:81]
	v_pk_mul_f32 v[114:115], v[114:115], v[82:83]
	v_cvt_pk_bf16_f32 v8, v120, v121
	v_cvt_pk_bf16_f32 v9, v122, v123
	v_cvt_pk_bf16_f32 v10, v112, v113
	v_cvt_pk_bf16_f32 v11, v114, v115
	global_store_dwordx4 v[0:1], v[8:11], off
	v_lshlrev_b32_e32 v120, 16, v28
	v_and_b32_e32 v121, 0xffff0000, v28
	v_lshlrev_b32_e32 v122, 16, v29
	v_and_b32_e32 v123, 0xffff0000, v29
	v_lshlrev_b32_e32 v112, 16, v30
	v_and_b32_e32 v113, 0xffff0000, v30
	v_lshlrev_b32_e32 v114, 16, v31
	v_and_b32_e32 v115, 0xffff0000, v31
	v_mul_f32_e32 v120, v120, v48
	v_mul_f32_e32 v121, v121, v48
	v_mul_f32_e32 v122, v122, v48
	v_mul_f32_e32 v123, v123, v48
	v_mul_f32_e32 v112, v112, v48
	v_mul_f32_e32 v113, v113, v48
	v_mul_f32_e32 v114, v114, v48
	v_mul_f32_e32 v115, v115, v48
	v_pk_mul_f32 v[120:121], v[120:121], v[72:73]
	v_pk_mul_f32 v[122:123], v[122:123], v[74:75]
	v_pk_mul_f32 v[112:113], v[112:113], v[64:65]
	v_pk_mul_f32 v[114:115], v[114:115], v[66:67]
	v_cvt_pk_bf16_f32 v8, v120, v121
	v_cvt_pk_bf16_f32 v9, v122, v123
	v_cvt_pk_bf16_f32 v10, v112, v113
	v_cvt_pk_bf16_f32 v11, v114, v115
	global_store_dwordx4 v[0:1], v[8:11], off offset:256
	v_lshl_add_u64 v[0:1], v[0:1], 0, s[64:65]
	v_lshlrev_b32_e32 v120, 16, v52
	v_and_b32_e32 v121, 0xffff0000, v52
	v_lshlrev_b32_e32 v122, 16, v53
	v_and_b32_e32 v123, 0xffff0000, v53
	v_lshlrev_b32_e32 v112, 16, v54
	v_and_b32_e32 v113, 0xffff0000, v54
	v_lshlrev_b32_e32 v114, 16, v55
	v_and_b32_e32 v115, 0xffff0000, v55
	v_mul_f32_e32 v120, v120, v49
	v_mul_f32_e32 v121, v121, v49
	v_mul_f32_e32 v122, v122, v49
	v_mul_f32_e32 v123, v123, v49
	v_mul_f32_e32 v112, v112, v49
	v_mul_f32_e32 v113, v113, v49
	v_mul_f32_e32 v114, v114, v49
	v_mul_f32_e32 v115, v115, v49
	v_pk_mul_f32 v[120:121], v[120:121], v[88:89]
	v_pk_mul_f32 v[122:123], v[122:123], v[90:91]
	v_pk_mul_f32 v[112:113], v[112:113], v[80:81]
	v_pk_mul_f32 v[114:115], v[114:115], v[82:83]
	v_cvt_pk_bf16_f32 v8, v120, v121
	v_cvt_pk_bf16_f32 v9, v122, v123
	v_cvt_pk_bf16_f32 v10, v112, v113
	v_cvt_pk_bf16_f32 v11, v114, v115
	global_store_dwordx4 v[0:1], v[8:11], off
	v_lshlrev_b32_e32 v120, 16, v20
	v_and_b32_e32 v121, 0xffff0000, v20
	v_lshlrev_b32_e32 v122, 16, v21
	v_and_b32_e32 v123, 0xffff0000, v21
	v_lshlrev_b32_e32 v112, 16, v22
	v_and_b32_e32 v113, 0xffff0000, v22
	v_lshlrev_b32_e32 v114, 16, v23
	v_and_b32_e32 v115, 0xffff0000, v23
	v_mul_f32_e32 v120, v120, v49
	v_mul_f32_e32 v121, v121, v49
	v_mul_f32_e32 v122, v122, v49
	v_mul_f32_e32 v123, v123, v49
	v_mul_f32_e32 v112, v112, v49
	v_mul_f32_e32 v113, v113, v49
	v_mul_f32_e32 v114, v114, v49
	v_mul_f32_e32 v115, v115, v49
; __device__ __forceinline__ unsigned pk2(float lo, float hi) { const f32x2 v = {lo, hi}; const hwbf16x2 b = __builtin_convertvector(v, hwbf16x2); return __builtin_bit_cast(unsigned, b); }
; __device__ __forceinline__ unsigned cvt_pk_bf16(float lo, float hi) { unsigned r; asm volatile("v_cvt_pk_bf16_f32 %0, %1, %2" : "=v"(r) : "v"(lo), "v"(hi)); return r; }
;     __device__ __forceinline__ void operator()(const f32x4 (&acc)[2][2][4][2], const Unit& u, int wr, int wc, int fr_in, int fq_in) const {
;     ...
;                 for (int m2 = 0; m2 < 2; ++m2) { const int m = 2 * mh + m2; const size_t off = off0 + (size_t)(ai * HALF + m * 16) * u.ldc;
; #pragma unroll
;                     for (int bj = 0; bj < 2; ++bj) { const f32x4 v0 = acc[ai][bj][m][0] + rv[m2][bj][0], v1 = acc[ai][bj][m][1] + rv[m2][bj][1];
;                         u32x4 w; w.x = cvt_pk_bf16(v0[0], v0[1]); w.y = cvt_pk_bf16(v0[2], v0[3]); w.z = cvt_pk_bf16(v1[0], v1[1]); w.w = cvt_pk_bf16(v1[2], v1[3]);
;                         *(u32x4*)(O + off + bj * HALF) = w; } }
; template <bool OUT_F32, bool IN_BF16>
; __device__ __forceinline__ void phase_rmsnorm(const void* Xv, const float* gain, void* out) {
;     ...
;         for (int r = 0; r < RPT; ++r) { const int m = m0 + r * NGW; if (m >= NTOK) continue;
; #pragma unroll
;             for (int j = 0; j < 4; ++j) { const f32x4 y0 = v[r][j][0] * rs[r] * g[j][0], y1 = v[r][j][1] * rs[r] * g[j][1];
;                 if (OUT_F32) { float* o = (float*)out + (size_t)m * DM + 8 * lane + 512 * j; *(f32x4*)o = y0; *(f32x4*)(o + 4) = y1; }
;                 else { u32x4 w; w.x = pk2(y0.x, y0.y); w.y = pk2(y0.z, y0.w); w.z = pk2(y1.x, y1.y); w.w = pk2(y1.z, y1.w); *(u32x4*)((bf16_t*)out + (size_t)m * DM + 8 * lane + 512 * j) = w; } } }
	v_pk_mul_f32 v[120:121], v[120:121], v[72:73]
	v_pk_mul_f32 v[122:123], v[122:123], v[74:75]
	v_pk_mul_f32 v[112:113], v[112:113], v[64:65]
	v_pk_mul_f32 v[114:115], v[114:115], v[66:67]
	v_cvt_pk_bf16_f32 v8, v120, v121
	v_cvt_pk_bf16_f32 v9, v122, v123
	v_cvt_pk_bf16_f32 v10, v112, v113
	v_cvt_pk_bf16_f32 v11, v114, v115
	global_store_dwordx4 v[0:1], v[8:11], off offset:256
	v_lshl_add_u64 v[0:1], v[0:1], 0, s[64:65]
	v_lshlrev_b32_e32 v120, 16, v44
	v_and_b32_e32 v121, 0xffff0000, v44
	v_lshlrev_b32_e32 v122, 16, v45
	v_and_b32_e32 v123, 0xffff0000, v45
	v_lshlrev_b32_e32 v112, 16, v46
	v_and_b32_e32 v113, 0xffff0000, v46
	v_lshlrev_b32_e32 v114, 16, v47
	v_and_b32_e32 v115, 0xffff0000, v47
	v_mul_f32_e32 v120, v120, v50
	v_mul_f32_e32 v121, v121, v50
	v_mul_f32_e32 v122, v122, v50
	v_mul_f32_e32 v123, v123, v50
	v_mul_f32_e32 v112, v112, v50
	v_mul_f32_e32 v113, v113, v50
	v_mul_f32_e32 v114, v114, v50
	v_mul_f32_e32 v115, v115, v50
	v_pk_mul_f32 v[120:121], v[120:121], v[88:89]
	v_pk_mul_f32 v[122:123], v[122:123], v[90:91]
	v_pk_mul_f32 v[112:113], v[112:113], v[80:81]
	v_pk_mul_f32 v[114:115], v[114:115], v[82:83]
	v_cvt_pk_bf16_f32 v8, v120, v121
	v_cvt_pk_bf16_f32 v9, v122, v123
	v_cvt_pk_bf16_f32 v10, v112, v113
	v_cvt_pk_bf16_f32 v11, v114, v115
	global_store_dwordx4 v[0:1], v[8:11], off
	v_lshlrev_b32_e32 v120, 16, v12
	v_and_b32_e32 v121, 0xffff0000, v12
	v_lshlrev_b32_e32 v122, 16, v13
	v_and_b32_e32 v123, 0xffff0000, v13
	v_lshlrev_b32_e32 v112, 16, v14
	v_and_b32_e32 v113, 0xffff0000, v14
	v_lshlrev_b32_e32 v114, 16, v15
	v_and_b32_e32 v115, 0xffff0000, v15
	v_mul_f32_e32 v120, v120, v50
	v_mul_f32_e32 v121, v121, v50
	v_mul_f32_e32 v122, v122, v50
	v_mul_f32_e32 v123, v123, v50
	v_mul_f32_e32 v112, v112, v50
	v_mul_f32_e32 v113, v113, v50
	v_mul_f32_e32 v114, v114, v50
	v_mul_f32_e32 v115, v115, v50
	v_pk_mul_f32 v[120:121], v[120:121], v[72:73]
	v_pk_mul_f32 v[122:123], v[122:123], v[74:75]
	v_pk_mul_f32 v[112:113], v[112:113], v[64:65]
	v_pk_mul_f32 v[114:115], v[114:115], v[66:67]
	v_cvt_pk_bf16_f32 v8, v120, v121
	v_cvt_pk_bf16_f32 v9, v122, v123
	v_cvt_pk_bf16_f32 v10, v112, v113
	v_cvt_pk_bf16_f32 v11, v114, v115
	global_store_dwordx4 v[0:1], v[8:11], off offset:256
	v_lshl_add_u64 v[0:1], v[0:1], 0, s[64:65]
	v_lshlrev_b32_e32 v120, 16, v36
	v_and_b32_e32 v121, 0xffff0000, v36
	v_lshlrev_b32_e32 v122, 16, v37
	v_and_b32_e32 v123, 0xffff0000, v37
	v_lshlrev_b32_e32 v112, 16, v38
	v_and_b32_e32 v113, 0xffff0000, v38
	v_lshlrev_b32_e32 v114, 16, v39
	v_and_b32_e32 v115, 0xffff0000, v39
	v_mul_f32_e32 v120, v120, v51
	v_mul_f32_e32 v121, v121, v51
	v_mul_f32_e32 v122, v122, v51
	v_mul_f32_e32 v123, v123, v51
	v_mul_f32_e32 v112, v112, v51
	v_mul_f32_e32 v113, v113, v51
	v_mul_f32_e32 v114, v114, v51
	v_mul_f32_e32 v115, v115, v51
	v_pk_mul_f32 v[120:121], v[120:121], v[88:89]
	v_pk_mul_f32 v[122:123], v[122:123], v[90:91]
	v_pk_mul_f32 v[112:113], v[112:113], v[80:81]
	v_pk_mul_f32 v[114:115], v[114:115], v[82:83]
	v_cvt_pk_bf16_f32 v8, v120, v121
	v_cvt_pk_bf16_f32 v9, v122, v123
	v_cvt_pk_bf16_f32 v10, v112, v113
	v_cvt_pk_bf16_f32 v11, v114, v115
	global_store_dwordx4 v[0:1], v[8:11], off
	v_lshlrev_b32_e32 v120, 16, v4
	v_and_b32_e32 v121, 0xffff0000, v4
	v_lshlrev_b32_e32 v122, 16, v5
	v_and_b32_e32 v123, 0xffff0000, v5
	v_lshlrev_b32_e32 v112, 16, v6
	v_and_b32_e32 v113, 0xffff0000, v6
	v_lshlrev_b32_e32 v114, 16, v7
	v_and_b32_e32 v115, 0xffff0000, v7
	v_mul_f32_e32 v120, v120, v51
	v_mul_f32_e32 v121, v121, v51
	v_mul_f32_e32 v122, v122, v51
	v_mul_f32_e32 v123, v123, v51
	v_mul_f32_e32 v112, v112, v51
	v_mul_f32_e32 v113, v113, v51
	v_mul_f32_e32 v114, v114, v51
	v_mul_f32_e32 v115, v115, v51
	v_pk_mul_f32 v[120:121], v[120:121], v[72:73]
	v_pk_mul_f32 v[122:123], v[122:123], v[74:75]
	v_pk_mul_f32 v[112:113], v[112:113], v[64:65]
	v_pk_mul_f32 v[114:115], v[114:115], v[66:67]
	v_cvt_pk_bf16_f32 v8, v120, v121
	v_cvt_pk_bf16_f32 v9, v122, v123
	v_cvt_pk_bf16_f32 v10, v112, v113
	v_cvt_pk_bf16_f32 v11, v114, v115
	global_store_dwordx4 v[0:1], v[8:11], off offset:256
	v_cmp_gt_u32_e32 vcc, 64, v185
	s_cbranch_vccnz .Lep_xb_done
	s_mov_b32 s0, 0x10000
	s_mov_b32 s1, 0
	v_mov_b32_e32 v0, v174
	v_mov_b32_e32 v1, v175
	global_store_dwordx4 v[0:1], v[124:127], off
	global_store_dwordx4 v[0:1], v[92:95], off offset:256
	v_lshl_add_u64 v[0:1], v[0:1], 0, s[0:1]
	global_store_dwordx4 v[0:1], v[116:119], off
	global_store_dwordx4 v[0:1], v[84:87], off offset:256
	v_lshl_add_u64 v[0:1], v[0:1], 0, s[0:1]
	global_store_dwordx4 v[0:1], v[108:111], off
	global_store_dwordx4 v[0:1], v[76:79], off offset:256
	v_lshl_add_u64 v[0:1], v[0:1], 0, s[0:1]
	global_store_dwordx4 v[0:1], v[100:103], off
	global_store_dwordx4 v[0:1], v[68:71], off offset:256
	s_mov_b32 s0, 0x50000
	v_lshl_add_u64 v[0:1], v[0:1], 0, s[0:1]
	s_mov_b32 s0, 0x10000
	global_store_dwordx4 v[0:1], v[60:63], off
	global_store_dwordx4 v[0:1], v[28:31], off offset:256
	v_lshl_add_u64 v[0:1], v[0:1], 0, s[0:1]
	global_store_dwordx4 v[0:1], v[52:55], off
	global_store_dwordx4 v[0:1], v[20:23], off offset:256
	v_lshl_add_u64 v[0:1], v[0:1], 0, s[0:1]
	global_store_dwordx4 v[0:1], v[44:47], off
	global_store_dwordx4 v[0:1], v[12:15], off offset:256
	v_lshl_add_u64 v[0:1], v[0:1], 0, s[0:1]
	global_store_dwordx4 v[0:1], v[36:39], off
	global_store_dwordx4 v[0:1], v[4:7], off offset:256
.Lep_xb_done:
	s_movk_i32 s56, 0x1f8
	s_movk_i32 s57, 0x1fff
	s_mov_b32 s58, 0x2c000
	s_mov_b32 s59, 0x84000
	s_mov_b32 s64, 0xb0000
	s_mov_b32 s65, 0xdc000
	s_mov_b64 vcc, s[100:101]
	v_readfirstlane_b32 s101, v185
	s_lshr_b32 s101, s101, 6
	s_min_u32 s101, s101, 1
	s_cbranch_vccnz .LBB0_282
	s_branch .Lln_ret
.Lw0_a:
	s_cmp_eq_u32 s101, 0
	s_cbranch_scc1 .Lw0_a_full
	s_waitcnt vmcnt(16)
	s_branch .Lw0_a_ret
.Lw0_a_full:
	s_waitcnt vmcnt(0)
	s_branch .Lw0_a_ret
.Lw0_b:
	s_cmp_eq_u32 s101, 0
	s_cbranch_scc1 .Lw0_b_full
	s_mov_b32 s101, 0
	s_waitcnt vmcnt(16) lgkmcnt(0)
	s_branch .Lw0_b_ret
.Lw0_b_full:
	s_waitcnt vmcnt(0) lgkmcnt(0)
	s_branch .Lw0_b_ret
